# deferred transposes: each block takes a contiguous range of units, even/odd interleaved so the four units in flight touch different memory channels
# speedup vs baseline: 1.0020x; 1.0018x over previous
.LBB0_289:
	s_sub_u32 s0, s94, s86
	s_bfe_u32 s1, s86, 0x30003
	s_mul_i32 s1, s1, s84
	s_cmp_lg_u32 s0, s1
	s_cbranch_scc1 .Ldt0_skip
	s_add_u32 s0, s84, 0x1207
	s_mov_b32 s1, 0
.Ldt0_kl:
	s_cmp_lt_u32 s0, s84
	s_cbranch_scc1 .Ldt0_kd
	s_sub_u32 s0, s0, s84
	s_add_u32 s1, s1, 1
	s_branch .Ldt0_kl
.Ldt0_kd:
	s_sub_u32 s24, s84, s86
	s_sub_u32 s24, s24, 1
	s_mul_i32 s24, s24, s1
	s_addk_i32 s24, 0xa08
	s_cmpk_ge_u32 s24, 0x1c10
	s_cbranch_scc1 .Ldt0_skip
	s_sub_u32 s9, 0x1c10, s24
	s_min_u32 s9, s9, s1
	s_add_u32 s16, s9, 1
	s_lshr_b32 s16, s16, 1
	s_mov_b32 s52, 0
	s_waitcnt lgkmcnt(0)
	s_barrier
	v_readlane_b32 s54, v254, 54
	v_readlane_b32 s55, v254, 55
	v_readlane_b32 s56, v253, 2
	v_readlane_b32 s57, v253, 3
	v_readlane_b32 s58, v253, 8
	v_readlane_b32 s59, v253, 9
	v_readlane_b32 s60, v253, 10
	v_readlane_b32 s61, v253, 11
	v_readlane_b32 s62, v254, 12
	v_readlane_b32 s63, v254, 13
	v_and_b32_e32 v106, 7, v180
	v_lshrrev_b32_e32 v93, 3, v180
	s_add_u32 s54, s54, 0xa080000
	s_addc_u32 s55, s55, 0
	s_add_u32 s58, s58, 0x5000000
	s_addc_u32 s59, s59, 0
	s_add_u32 s60, s60, 0x40000
	s_addc_u32 s61, s61, 0
	v_lshlrev_b32_e32 v94, 4, v106
	v_bfe_u32 v107, v180, 3, 1
	v_lshlrev_b32_e32 v108, 2, v106
	v_lshl_add_u32 v108, v107, 1, v108
	v_mul_u32_u24_e32 v84, 0x410, v108
	v_lshrrev_b32_e32 v109, 3, v93
	v_xor_b32_e32 v109, v109, v106
	v_lshlrev_b32_e32 v109, 3, v109
	v_and_b32_e32 v110, 6, v93
	v_or_b32_e32 v109, v109, v110
	v_lshl_add_u32 v84, v109, 1, v84
	v_cmp_ne_u32_e64 s[74:75], 0, v107
	v_mov_b32_e32 v104, 0x1000504
	v_mov_b32_e32 v105, 0x3020706
	v_mov_b32_e32 v111, 0x5040100
	v_mov_b32_e32 v112, 0x7060302
	v_cndmask_b32_e64 v104, v104, v111, s[74:75]
	v_cndmask_b32_e64 v105, v105, v112, s[74:75]
	v_lshrrev_b32_e32 v106, 6, v180
	v_and_b32_e32 v107, 63, v180
	v_lshrrev_b32_e32 v108, 2, v106
	v_add_u32_e32 v109, 0, v108
	v_xor_b32_e32 v109, v109, v107
	v_lshlrev_b32_e32 v109, 4, v109
	v_add_u32_e32 v110, 0, v106
	v_mul_u32_u24_e32 v110, 0x410, v110
	v_add_u32_e32 v85, v109, v110
	v_add_u32_e32 v109, 2, v108
	v_xor_b32_e32 v109, v109, v107
	v_lshlrev_b32_e32 v109, 4, v109
	v_add_u32_e32 v110, 8, v106
	v_mul_u32_u24_e32 v110, 0x410, v110
	v_add_u32_e32 v86, v109, v110
	v_add_u32_e32 v109, 4, v108
	v_xor_b32_e32 v109, v109, v107
	v_lshlrev_b32_e32 v109, 4, v109
	v_add_u32_e32 v110, 16, v106
	v_mul_u32_u24_e32 v110, 0x410, v110
	v_add_u32_e32 v87, v109, v110
	v_add_u32_e32 v109, 6, v108
	v_xor_b32_e32 v109, v109, v107
	v_lshlrev_b32_e32 v109, 4, v109
	v_add_u32_e32 v110, 24, v106
	v_mul_u32_u24_e32 v110, 0x410, v110
	v_add_u32_e32 v88, v109, v110
	v_lshlrev_b32_e32 v109, 13, v106
	v_lshl_add_u32 v89, v107, 4, v109
	v_add_u32_e32 v90, 0x10000, v89
	v_add_u32_e32 v91, 0x20000, v89
	v_add_u32_e32 v92, 0x30000, v89
	s_mov_b32 s53, 0
	s_mov_b32 s72, 0
	s_mov_b32 s73, 0
	s_mov_b32 s12, 0
	s_mov_b32 s13, 0
	s_cmp_lt_u32 s52, s16
	s_cbranch_scc1 .Ldt0_ev0
	s_sub_u32 s8, s52, s16
	s_lshl_b32 s8, s8, 1
	s_add_u32 s8, s8, 1
	s_branch .Ldt0_jd0
.Ldt0_ev0:
	s_lshl_b32 s8, s52, 1
.Ldt0_jd0:
	s_add_u32 s8, s8, s24
	s_cmpk_ge_u32 s8, 0x1410
	s_cbranch_scc1 .Ldt0_out0
	s_sub_i32 s0, s8, 0xa08
	s_mul_i32 s1, s0, 0xcc3
	s_lshr_b32 s1, s1, 20
	s_mul_i32 s2, s1, 0x141
	s_sub_u32 s2, s0, s2
	s_lshl_b32 s3, s2, 7
	s_mul_i32 s4, s1, 0x1410000
	s_add_u32 s3, s3, s4
	s_add_u32 s64, s54, s3
	s_addc_u32 s65, s55, 0
	s_mov_b32 s7, 0xa080
	s_lshl_b32 s4, s1, 10
	s_cmpk_lt_u32 s2, 0x80
	s_cbranch_scc1 .Ldt0_wlo0
	s_cmpk_eq_u32 s2, 0x80
	s_cbranch_scc1 .Ldt0_wlr0
	s_add_i32 s2, s2, -1

.Ldt0_out0:
	s_sub_i32 s0, s8, 0x1410
	s_lshr_b32 s1, s0, 10
	s_bfe_u32 s2, s0, 0x30007
	s_and_b32 s3, s0, 0x7f
	s_lshl_b32 s4, s1, 26
	s_lshl_b32 s5, s3, 7
	s_add_u32 s4, s4, s5
	s_lshl_b32 s5, s2, 23
	s_add_u32 s4, s4, s5
	s_add_u32 s64, s56, s4
	s_addc_u32 s65, s57, 0
	s_lshl_b32 s4, s1, 25
	s_lshl_b32 s5, s3, 18
	s_add_u32 s4, s4, s5
	s_lshl_b32 s5, s2, 10
	s_add_u32 s4, s4, s5
	s_add_u32 s66, s62, s4
	s_addc_u32 s67, s63, 0
	s_movk_i32 s7, 0x4000
.Ldt0_ud0:
	v_mul_u32_u24_e32 v96, s7, v93
	s_lshl_b32 s6, s7, 6
	v_add_u32_e32 v96, v96, v94
	v_add_u32_e32 v97, s6, v96
	v_add_u32_e32 v98, s6, v97
	v_add_u32_e32 v99, s6, v98
	v_add_u32_e32 v100, s6, v99
	v_add_u32_e32 v101, s6, v100
	v_add_u32_e32 v102, s6, v101
	v_add_u32_e32 v103, s6, v102
	global_load_dwordx4 v[4:7], v96, s[64:65] nt
	global_load_dwordx4 v[8:11], v97, s[64:65] nt
	global_load_dwordx4 v[12:15], v98, s[64:65] nt
	global_load_dwordx4 v[16:19], v99, s[64:65] nt
	global_load_dwordx4 v[20:23], v100, s[64:65] nt
	global_load_dwordx4 v[24:27], v101, s[64:65] nt
	global_load_dwordx4 v[28:31], v102, s[64:65] nt
	global_load_dwordx4 v[32:35], v103, s[64:65] nt
	s_mov_b32 s72, 1
	s_add_u32 s52, s52, 1
	s_cmp_ge_u32 s52, s9
	s_cbranch_scc1 .Ldt0_proc0
	s_cmp_lt_u32 s52, s16
	s_cbranch_scc1 .Ldt0_ev1
	s_sub_u32 s8, s52, s16
	s_lshl_b32 s8, s8, 1
	s_add_u32 s8, s8, 1
	s_branch .Ldt0_jd1

.Ldt0_out1:
	s_sub_i32 s0, s8, 0x1410
	s_lshr_b32 s1, s0, 10
	s_bfe_u32 s2, s0, 0x30007
	s_and_b32 s3, s0, 0x7f
	s_lshl_b32 s4, s1, 26
	s_lshl_b32 s5, s3, 7
	s_add_u32 s4, s4, s5
	s_lshl_b32 s5, s2, 23
	s_add_u32 s4, s4, s5
	s_add_u32 s64, s56, s4
	s_addc_u32 s65, s57, 0
	s_lshl_b32 s4, s1, 25
	s_lshl_b32 s5, s3, 18
	s_add_u32 s4, s4, s5
	s_lshl_b32 s5, s2, 10
	s_add_u32 s4, s4, s5
	s_add_u32 s10, s62, s4
	s_addc_u32 s11, s63, 0
	s_movk_i32 s7, 0x4000
.Ldt0_ud1:
	v_mul_u32_u24_e32 v96, s7, v93
	s_lshl_b32 s6, s7, 6
	v_add_u32_e32 v96, v96, v94
	v_add_u32_e32 v97, s6, v96
	v_add_u32_e32 v98, s6, v97
	v_add_u32_e32 v99, s6, v98
	v_add_u32_e32 v100, s6, v99
	v_add_u32_e32 v101, s6, v100
	v_add_u32_e32 v102, s6, v101
	v_add_u32_e32 v103, s6, v102
	global_load_dwordx4 v[36:39], v96, s[64:65] nt
	global_load_dwordx4 v[40:43], v97, s[64:65] nt
	global_load_dwordx4 v[44:47], v98, s[64:65] nt
	global_load_dwordx4 v[48:51], v99, s[64:65] nt
	global_load_dwordx4 v[52:55], v100, s[64:65] nt
	global_load_dwordx4 v[56:59], v101, s[64:65] nt
	global_load_dwordx4 v[60:63], v102, s[64:65] nt
	global_load_dwordx4 v[64:67], v103, s[64:65] nt
	s_mov_b32 s73, 1
	s_add_u32 s52, s52, 1
	s_cmp_ge_u32 s52, s9
	s_cbranch_scc1 .Ldt0_proc0
	s_cmp_lt_u32 s52, s16
	s_cbranch_scc1 .Ldt0_ev2
	s_sub_u32 s8, s52, s16
	s_lshl_b32 s8, s8, 1
	s_add_u32 s8, s8, 1
	s_branch .Ldt0_jd2

.Ldt0_out2:
	s_sub_i32 s0, s8, 0x1410
	s_lshr_b32 s1, s0, 10
	s_bfe_u32 s2, s0, 0x30007
	s_and_b32 s3, s0, 0x7f
	s_lshl_b32 s4, s1, 26
	s_lshl_b32 s5, s3, 7
	s_add_u32 s4, s4, s5
	s_lshl_b32 s5, s2, 23
	s_add_u32 s4, s4, s5
	s_add_u32 s64, s56, s4
	s_addc_u32 s65, s57, 0
	s_lshl_b32 s4, s1, 25
	s_lshl_b32 s5, s3, 18
	s_add_u32 s4, s4, s5
	s_lshl_b32 s5, s2, 10
	s_add_u32 s4, s4, s5
	s_add_u32 s14, s62, s4
	s_addc_u32 s15, s63, 0
	s_movk_i32 s7, 0x4000
.Ldt0_ud2:
	v_mul_u32_u24_e32 v96, s7, v93
	s_lshl_b32 s6, s7, 6
	v_add_u32_e32 v96, v96, v94
	v_add_u32_e32 v97, s6, v96
	v_add_u32_e32 v98, s6, v97
	v_add_u32_e32 v99, s6, v98
	v_add_u32_e32 v100, s6, v99
	v_add_u32_e32 v101, s6, v100
	v_add_u32_e32 v102, s6, v101
	v_add_u32_e32 v103, s6, v102
	global_load_dwordx4 v[130:133], v96, s[64:65] nt
	global_load_dwordx4 v[134:137], v97, s[64:65] nt
	global_load_dwordx4 v[138:141], v98, s[64:65] nt
	global_load_dwordx4 v[142:145], v99, s[64:65] nt
	global_load_dwordx4 v[146:149], v100, s[64:65] nt
	global_load_dwordx4 v[150:153], v101, s[64:65] nt
	global_load_dwordx4 v[154:157], v102, s[64:65] nt
	global_load_dwordx4 v[158:161], v103, s[64:65] nt
	s_mov_b32 s12, 1
	s_add_u32 s52, s52, 1
	s_cmp_ge_u32 s52, s9
	s_cbranch_scc1 .Ldt0_proc0
	s_cmp_lt_u32 s52, s16
	s_cbranch_scc1 .Ldt0_ev3
	s_sub_u32 s8, s52, s16
	s_lshl_b32 s8, s8, 1
	s_add_u32 s8, s8, 1
	s_branch .Ldt0_jd3

.Ldt0_out3:
	s_sub_i32 s0, s8, 0x1410
	s_lshr_b32 s1, s0, 10
	s_bfe_u32 s2, s0, 0x30007
	s_and_b32 s3, s0, 0x7f
	s_lshl_b32 s4, s1, 26
	s_lshl_b32 s5, s3, 7
	s_add_u32 s4, s4, s5
	s_lshl_b32 s5, s2, 23
	s_add_u32 s4, s4, s5
	s_add_u32 s64, s56, s4
	s_addc_u32 s65, s57, 0
	s_lshl_b32 s4, s1, 25
	s_lshl_b32 s5, s3, 18
	s_add_u32 s4, s4, s5
	s_lshl_b32 s5, s2, 10
	s_add_u32 s4, s4, s5
	s_add_u32 s90, s62, s4
	s_addc_u32 s91, s63, 0
	s_movk_i32 s7, 0x4000
.Ldt0_ud3:
	v_mul_u32_u24_e32 v96, s7, v93
	s_lshl_b32 s6, s7, 6
	v_add_u32_e32 v96, v96, v94
	v_add_u32_e32 v97, s6, v96
	v_add_u32_e32 v98, s6, v97
	v_add_u32_e32 v99, s6, v98
	v_add_u32_e32 v100, s6, v99
	v_add_u32_e32 v101, s6, v100
	v_add_u32_e32 v102, s6, v101
	v_add_u32_e32 v103, s6, v102
	global_load_dwordx4 v[182:185], v96, s[64:65] nt
	global_load_dwordx4 v[186:189], v97, s[64:65] nt
	global_load_dwordx4 v[190:193], v98, s[64:65] nt
	global_load_dwordx4 v[194:197], v99, s[64:65] nt
	global_load_dwordx4 v[198:201], v100, s[64:65] nt
	global_load_dwordx4 v[202:205], v101, s[64:65] nt
	global_load_dwordx4 v[206:209], v102, s[64:65] nt
	global_load_dwordx4 v[210:213], v103, s[64:65] nt
	s_mov_b32 s13, 1
	s_add_u32 s52, s52, 1

.Ldt0_wd0:
	v_cvt_pk_bf16_f32 v4, v4, v5
	v_cvt_pk_bf16_f32 v6, v6, v7
	v_cvt_pk_bf16_f32 v8, v8, v9
	v_cvt_pk_bf16_f32 v10, v10, v11
	v_cvt_pk_bf16_f32 v12, v12, v13
	v_cvt_pk_bf16_f32 v14, v14, v15
	v_cvt_pk_bf16_f32 v16, v16, v17
	v_cvt_pk_bf16_f32 v18, v18, v19
	v_cvt_pk_bf16_f32 v20, v20, v21
	v_cvt_pk_bf16_f32 v22, v22, v23
	v_cvt_pk_bf16_f32 v24, v24, v25
	v_cvt_pk_bf16_f32 v26, v26, v27
	v_cvt_pk_bf16_f32 v28, v28, v29
	v_cvt_pk_bf16_f32 v30, v30, v31
	v_cvt_pk_bf16_f32 v32, v32, v33
	v_cvt_pk_bf16_f32 v34, v34, v35
	v_cndmask_b32_e64 v5, v6, v4, s[74:75]
	v_cndmask_b32_e64 v7, v4, v6, s[74:75]
	v_cndmask_b32_e64 v9, v10, v8, s[74:75]
	v_cndmask_b32_e64 v11, v8, v10, s[74:75]
	v_cndmask_b32_e64 v13, v14, v12, s[74:75]
	v_cndmask_b32_e64 v15, v12, v14, s[74:75]
	v_cndmask_b32_e64 v17, v18, v16, s[74:75]
	v_cndmask_b32_e64 v19, v16, v18, s[74:75]
	v_cndmask_b32_e64 v21, v22, v20, s[74:75]
	v_cndmask_b32_e64 v23, v20, v22, s[74:75]
	v_cndmask_b32_e64 v25, v26, v24, s[74:75]
	v_cndmask_b32_e64 v27, v24, v26, s[74:75]
	v_cndmask_b32_e64 v29, v30, v28, s[74:75]
	v_cndmask_b32_e64 v31, v28, v30, s[74:75]
	v_cndmask_b32_e64 v33, v34, v32, s[74:75]
	v_cndmask_b32_e64 v35, v32, v34, s[74:75]
	v_mov_b32_dpp v4, v5 row_ror:8 row_mask:0xf bank_mask:0xf
	v_mov_b32_dpp v8, v9 row_ror:8 row_mask:0xf bank_mask:0xf
	v_mov_b32_dpp v12, v13 row_ror:8 row_mask:0xf bank_mask:0xf
	v_mov_b32_dpp v16, v17 row_ror:8 row_mask:0xf bank_mask:0xf
	v_mov_b32_dpp v20, v21 row_ror:8 row_mask:0xf bank_mask:0xf
	v_mov_b32_dpp v24, v25 row_ror:8 row_mask:0xf bank_mask:0xf
	v_mov_b32_dpp v28, v29 row_ror:8 row_mask:0xf bank_mask:0xf
	v_mov_b32_dpp v32, v33 row_ror:8 row_mask:0xf bank_mask:0xf
	s_nop 1
	v_perm_b32 v68, v7, v4, v104
	v_perm_b32 v69, v7, v4, v105
	v_perm_b32 v70, v11, v8, v104
	v_perm_b32 v71, v11, v8, v105
	v_perm_b32 v72, v15, v12, v104
	v_perm_b32 v73, v15, v12, v105
	v_perm_b32 v74, v19, v16, v104
	v_perm_b32 v75, v19, v16, v105
	v_perm_b32 v76, v23, v20, v104
	v_perm_b32 v77, v23, v20, v105
	v_perm_b32 v78, v27, v24, v104
	v_perm_b32 v79, v27, v24, v105
	v_perm_b32 v80, v31, v28, v104
	v_perm_b32 v81, v31, v28, v105
	v_perm_b32 v82, v35, v32, v104
	v_perm_b32 v83, v35, v32, v105
	s_mov_b64 s[70:71], s[66:67]
	s_mov_b32 s72, 0
	s_cmp_ge_u32 s52, s9
	s_cbranch_scc1 .Ldt0_nl0
	s_cmp_lt_u32 s52, s16
	s_cbranch_scc1 .Ldt0_ev4
	s_sub_u32 s8, s52, s16
	s_lshl_b32 s8, s8, 1
	s_add_u32 s8, s8, 1
	s_branch .Ldt0_jd4

.Ldt0_ud4:
	v_mul_u32_u24_e32 v96, s7, v93
	s_lshl_b32 s6, s7, 6
	v_add_u32_e32 v96, v96, v94
	v_add_u32_e32 v97, s6, v96
	v_add_u32_e32 v98, s6, v97
	v_add_u32_e32 v99, s6, v98
	v_add_u32_e32 v100, s6, v99
	v_add_u32_e32 v101, s6, v100
	v_add_u32_e32 v102, s6, v101
	v_add_u32_e32 v103, s6, v102
	global_load_dwordx4 v[4:7], v96, s[64:65] nt
	global_load_dwordx4 v[8:11], v97, s[64:65] nt
	global_load_dwordx4 v[12:15], v98, s[64:65] nt
	global_load_dwordx4 v[16:19], v99, s[64:65] nt
	global_load_dwordx4 v[20:23], v100, s[64:65] nt
	global_load_dwordx4 v[24:27], v101, s[64:65] nt
	global_load_dwordx4 v[28:31], v102, s[64:65] nt
	global_load_dwordx4 v[32:35], v103, s[64:65] nt
	s_mov_b32 s72, 1
	s_add_u32 s52, s52, 1

.Ldt0_wd1:
	v_cvt_pk_bf16_f32 v36, v36, v37
	v_cvt_pk_bf16_f32 v38, v38, v39
	v_cvt_pk_bf16_f32 v40, v40, v41
	v_cvt_pk_bf16_f32 v42, v42, v43
	v_cvt_pk_bf16_f32 v44, v44, v45
	v_cvt_pk_bf16_f32 v46, v46, v47
	v_cvt_pk_bf16_f32 v48, v48, v49
	v_cvt_pk_bf16_f32 v50, v50, v51
	v_cvt_pk_bf16_f32 v52, v52, v53
	v_cvt_pk_bf16_f32 v54, v54, v55
	v_cvt_pk_bf16_f32 v56, v56, v57
	v_cvt_pk_bf16_f32 v58, v58, v59
	v_cvt_pk_bf16_f32 v60, v60, v61
	v_cvt_pk_bf16_f32 v62, v62, v63
	v_cvt_pk_bf16_f32 v64, v64, v65
	v_cvt_pk_bf16_f32 v66, v66, v67
	v_cndmask_b32_e64 v37, v38, v36, s[74:75]
	v_cndmask_b32_e64 v39, v36, v38, s[74:75]
	v_cndmask_b32_e64 v41, v42, v40, s[74:75]
	v_cndmask_b32_e64 v43, v40, v42, s[74:75]
	v_cndmask_b32_e64 v45, v46, v44, s[74:75]
	v_cndmask_b32_e64 v47, v44, v46, s[74:75]
	v_cndmask_b32_e64 v49, v50, v48, s[74:75]
	v_cndmask_b32_e64 v51, v48, v50, s[74:75]
	v_cndmask_b32_e64 v53, v54, v52, s[74:75]
	v_cndmask_b32_e64 v55, v52, v54, s[74:75]
	v_cndmask_b32_e64 v57, v58, v56, s[74:75]
	v_cndmask_b32_e64 v59, v56, v58, s[74:75]
	v_cndmask_b32_e64 v61, v62, v60, s[74:75]
	v_cndmask_b32_e64 v63, v60, v62, s[74:75]
	v_cndmask_b32_e64 v65, v66, v64, s[74:75]
	v_cndmask_b32_e64 v67, v64, v66, s[74:75]
	v_mov_b32_dpp v36, v37 row_ror:8 row_mask:0xf bank_mask:0xf
	v_mov_b32_dpp v40, v41 row_ror:8 row_mask:0xf bank_mask:0xf
	v_mov_b32_dpp v44, v45 row_ror:8 row_mask:0xf bank_mask:0xf
	v_mov_b32_dpp v48, v49 row_ror:8 row_mask:0xf bank_mask:0xf
	v_mov_b32_dpp v52, v53 row_ror:8 row_mask:0xf bank_mask:0xf
	v_mov_b32_dpp v56, v57 row_ror:8 row_mask:0xf bank_mask:0xf
	v_mov_b32_dpp v60, v61 row_ror:8 row_mask:0xf bank_mask:0xf
	v_mov_b32_dpp v64, v65 row_ror:8 row_mask:0xf bank_mask:0xf
	s_nop 1
	v_perm_b32 v68, v39, v36, v104
	v_perm_b32 v69, v39, v36, v105
	v_perm_b32 v70, v43, v40, v104
	v_perm_b32 v71, v43, v40, v105
	v_perm_b32 v72, v47, v44, v104
	v_perm_b32 v73, v47, v44, v105
	v_perm_b32 v74, v51, v48, v104
	v_perm_b32 v75, v51, v48, v105
	v_perm_b32 v76, v55, v52, v104
	v_perm_b32 v77, v55, v52, v105
	v_perm_b32 v78, v59, v56, v104
	v_perm_b32 v79, v59, v56, v105
	v_perm_b32 v80, v63, v60, v104
	v_perm_b32 v81, v63, v60, v105
	v_perm_b32 v82, v67, v64, v104
	v_perm_b32 v83, v67, v64, v105
	s_mov_b64 s[70:71], s[10:11]
	s_mov_b32 s73, 0
	s_cmp_ge_u32 s52, s9
	s_cbranch_scc1 .Ldt0_nl1
	s_cmp_lt_u32 s52, s16
	s_cbranch_scc1 .Ldt0_ev5
	s_sub_u32 s8, s52, s16
	s_lshl_b32 s8, s8, 1
	s_add_u32 s8, s8, 1
	s_branch .Ldt0_jd5

.Ldt0_ud5:
	v_mul_u32_u24_e32 v96, s7, v93
	s_lshl_b32 s6, s7, 6
	v_add_u32_e32 v96, v96, v94
	v_add_u32_e32 v97, s6, v96
	v_add_u32_e32 v98, s6, v97
	v_add_u32_e32 v99, s6, v98
	v_add_u32_e32 v100, s6, v99
	v_add_u32_e32 v101, s6, v100
	v_add_u32_e32 v102, s6, v101
	v_add_u32_e32 v103, s6, v102
	global_load_dwordx4 v[36:39], v96, s[64:65] nt
	global_load_dwordx4 v[40:43], v97, s[64:65] nt
	global_load_dwordx4 v[44:47], v98, s[64:65] nt
	global_load_dwordx4 v[48:51], v99, s[64:65] nt
	global_load_dwordx4 v[52:55], v100, s[64:65] nt
	global_load_dwordx4 v[56:59], v101, s[64:65] nt
	global_load_dwordx4 v[60:63], v102, s[64:65] nt
	global_load_dwordx4 v[64:67], v103, s[64:65] nt
	s_mov_b32 s73, 1
	s_add_u32 s52, s52, 1

.Ldt0_wd2:
	v_cvt_pk_bf16_f32 v130, v130, v131
	v_cvt_pk_bf16_f32 v132, v132, v133
	v_cvt_pk_bf16_f32 v134, v134, v135
	v_cvt_pk_bf16_f32 v136, v136, v137
	v_cvt_pk_bf16_f32 v138, v138, v139
	v_cvt_pk_bf16_f32 v140, v140, v141
	v_cvt_pk_bf16_f32 v142, v142, v143
	v_cvt_pk_bf16_f32 v144, v144, v145
	v_cvt_pk_bf16_f32 v146, v146, v147
	v_cvt_pk_bf16_f32 v148, v148, v149
	v_cvt_pk_bf16_f32 v150, v150, v151
	v_cvt_pk_bf16_f32 v152, v152, v153
	v_cvt_pk_bf16_f32 v154, v154, v155
	v_cvt_pk_bf16_f32 v156, v156, v157
	v_cvt_pk_bf16_f32 v158, v158, v159
	v_cvt_pk_bf16_f32 v160, v160, v161
	v_cndmask_b32_e64 v131, v132, v130, s[74:75]
	v_cndmask_b32_e64 v133, v130, v132, s[74:75]
	v_cndmask_b32_e64 v135, v136, v134, s[74:75]
	v_cndmask_b32_e64 v137, v134, v136, s[74:75]
	v_cndmask_b32_e64 v139, v140, v138, s[74:75]
	v_cndmask_b32_e64 v141, v138, v140, s[74:75]
	v_cndmask_b32_e64 v143, v144, v142, s[74:75]
	v_cndmask_b32_e64 v145, v142, v144, s[74:75]
	v_cndmask_b32_e64 v147, v148, v146, s[74:75]
	v_cndmask_b32_e64 v149, v146, v148, s[74:75]
	v_cndmask_b32_e64 v151, v152, v150, s[74:75]
	v_cndmask_b32_e64 v153, v150, v152, s[74:75]
	v_cndmask_b32_e64 v155, v156, v154, s[74:75]
	v_cndmask_b32_e64 v157, v154, v156, s[74:75]
	v_cndmask_b32_e64 v159, v160, v158, s[74:75]
	v_cndmask_b32_e64 v161, v158, v160, s[74:75]
	v_mov_b32_dpp v130, v131 row_ror:8 row_mask:0xf bank_mask:0xf
	v_mov_b32_dpp v134, v135 row_ror:8 row_mask:0xf bank_mask:0xf
	v_mov_b32_dpp v138, v139 row_ror:8 row_mask:0xf bank_mask:0xf
	v_mov_b32_dpp v142, v143 row_ror:8 row_mask:0xf bank_mask:0xf
	v_mov_b32_dpp v146, v147 row_ror:8 row_mask:0xf bank_mask:0xf
	v_mov_b32_dpp v150, v151 row_ror:8 row_mask:0xf bank_mask:0xf
	v_mov_b32_dpp v154, v155 row_ror:8 row_mask:0xf bank_mask:0xf
	v_mov_b32_dpp v158, v159 row_ror:8 row_mask:0xf bank_mask:0xf
	s_nop 1
	v_perm_b32 v68, v133, v130, v104
	v_perm_b32 v69, v133, v130, v105
	v_perm_b32 v70, v137, v134, v104
	v_perm_b32 v71, v137, v134, v105
	v_perm_b32 v72, v141, v138, v104
	v_perm_b32 v73, v141, v138, v105
	v_perm_b32 v74, v145, v142, v104
	v_perm_b32 v75, v145, v142, v105
	v_perm_b32 v76, v149, v146, v104
	v_perm_b32 v77, v149, v146, v105
	v_perm_b32 v78, v153, v150, v104
	v_perm_b32 v79, v153, v150, v105
	v_perm_b32 v80, v157, v154, v104
	v_perm_b32 v81, v157, v154, v105
	v_perm_b32 v82, v161, v158, v104
	v_perm_b32 v83, v161, v158, v105
	s_mov_b64 s[70:71], s[14:15]
	s_mov_b32 s12, 0
	s_cmp_ge_u32 s52, s9
	s_cbranch_scc1 .Ldt0_nl2
	s_cmp_lt_u32 s52, s16
	s_cbranch_scc1 .Ldt0_ev6
	s_sub_u32 s8, s52, s16
	s_lshl_b32 s8, s8, 1
	s_add_u32 s8, s8, 1
	s_branch .Ldt0_jd6

.Ldt0_ud6:
	v_mul_u32_u24_e32 v96, s7, v93
	s_lshl_b32 s6, s7, 6
	v_add_u32_e32 v96, v96, v94
	v_add_u32_e32 v97, s6, v96
	v_add_u32_e32 v98, s6, v97
	v_add_u32_e32 v99, s6, v98
	v_add_u32_e32 v100, s6, v99
	v_add_u32_e32 v101, s6, v100
	v_add_u32_e32 v102, s6, v101
	v_add_u32_e32 v103, s6, v102
	global_load_dwordx4 v[130:133], v96, s[64:65] nt
	global_load_dwordx4 v[134:137], v97, s[64:65] nt
	global_load_dwordx4 v[138:141], v98, s[64:65] nt
	global_load_dwordx4 v[142:145], v99, s[64:65] nt
	global_load_dwordx4 v[146:149], v100, s[64:65] nt
	global_load_dwordx4 v[150:153], v101, s[64:65] nt
	global_load_dwordx4 v[154:157], v102, s[64:65] nt
	global_load_dwordx4 v[158:161], v103, s[64:65] nt
	s_mov_b32 s12, 1
	s_add_u32 s52, s52, 1

.Ldt0_wd3:
	v_cvt_pk_bf16_f32 v182, v182, v183
	v_cvt_pk_bf16_f32 v184, v184, v185
	v_cvt_pk_bf16_f32 v186, v186, v187
	v_cvt_pk_bf16_f32 v188, v188, v189
	v_cvt_pk_bf16_f32 v190, v190, v191
	v_cvt_pk_bf16_f32 v192, v192, v193
	v_cvt_pk_bf16_f32 v194, v194, v195
	v_cvt_pk_bf16_f32 v196, v196, v197
	v_cvt_pk_bf16_f32 v198, v198, v199
	v_cvt_pk_bf16_f32 v200, v200, v201
	v_cvt_pk_bf16_f32 v202, v202, v203
	v_cvt_pk_bf16_f32 v204, v204, v205
	v_cvt_pk_bf16_f32 v206, v206, v207
	v_cvt_pk_bf16_f32 v208, v208, v209
	v_cvt_pk_bf16_f32 v210, v210, v211
	v_cvt_pk_bf16_f32 v212, v212, v213
	v_cndmask_b32_e64 v183, v184, v182, s[74:75]
	v_cndmask_b32_e64 v185, v182, v184, s[74:75]
	v_cndmask_b32_e64 v187, v188, v186, s[74:75]
	v_cndmask_b32_e64 v189, v186, v188, s[74:75]
	v_cndmask_b32_e64 v191, v192, v190, s[74:75]
	v_cndmask_b32_e64 v193, v190, v192, s[74:75]
	v_cndmask_b32_e64 v195, v196, v194, s[74:75]
	v_cndmask_b32_e64 v197, v194, v196, s[74:75]
	v_cndmask_b32_e64 v199, v200, v198, s[74:75]
	v_cndmask_b32_e64 v201, v198, v200, s[74:75]
	v_cndmask_b32_e64 v203, v204, v202, s[74:75]
	v_cndmask_b32_e64 v205, v202, v204, s[74:75]
	v_cndmask_b32_e64 v207, v208, v206, s[74:75]
	v_cndmask_b32_e64 v209, v206, v208, s[74:75]
	v_cndmask_b32_e64 v211, v212, v210, s[74:75]
	v_cndmask_b32_e64 v213, v210, v212, s[74:75]
	v_mov_b32_dpp v182, v183 row_ror:8 row_mask:0xf bank_mask:0xf
	v_mov_b32_dpp v186, v187 row_ror:8 row_mask:0xf bank_mask:0xf
	v_mov_b32_dpp v190, v191 row_ror:8 row_mask:0xf bank_mask:0xf
	v_mov_b32_dpp v194, v195 row_ror:8 row_mask:0xf bank_mask:0xf
	v_mov_b32_dpp v198, v199 row_ror:8 row_mask:0xf bank_mask:0xf
	v_mov_b32_dpp v202, v203 row_ror:8 row_mask:0xf bank_mask:0xf
	v_mov_b32_dpp v206, v207 row_ror:8 row_mask:0xf bank_mask:0xf
	v_mov_b32_dpp v210, v211 row_ror:8 row_mask:0xf bank_mask:0xf
	s_nop 1
	v_perm_b32 v68, v185, v182, v104
	v_perm_b32 v69, v185, v182, v105
	v_perm_b32 v70, v189, v186, v104
	v_perm_b32 v71, v189, v186, v105
	v_perm_b32 v72, v193, v190, v104
	v_perm_b32 v73, v193, v190, v105
	v_perm_b32 v74, v197, v194, v104
	v_perm_b32 v75, v197, v194, v105
	v_perm_b32 v76, v201, v198, v104
	v_perm_b32 v77, v201, v198, v105
	v_perm_b32 v78, v205, v202, v104
	v_perm_b32 v79, v205, v202, v105
	v_perm_b32 v80, v209, v206, v104
	v_perm_b32 v81, v209, v206, v105
	v_perm_b32 v82, v213, v210, v104
	v_perm_b32 v83, v213, v210, v105
	s_mov_b64 s[70:71], s[90:91]
	s_mov_b32 s13, 0
	s_cmp_ge_u32 s52, s9
	s_cbranch_scc1 .Ldt0_nl3
	s_cmp_lt_u32 s52, s16
	s_cbranch_scc1 .Ldt0_ev7
	s_sub_u32 s8, s52, s16
	s_lshl_b32 s8, s8, 1
	s_add_u32 s8, s8, 1
	s_branch .Ldt0_jd7
